# P1: VMEM drain before the weight-copy tail removed (the seam behind it drains again; no LDS use in between) so the tail's first loads are issued without waiting for the last GEMM stores
# speedup vs baseline: 1.0022x; 1.0022x over previous
; #define PG8_WAIT_V(n) asm volatile("s_waitcnt vmcnt(" #n ")" ::: "memory")
; #define PG8_BAR __builtin_amdgcn_s_barrier()
;     ...
;     PG8_WAIT_V(0);
;     if constexpr (!ALIGN_EPI) { if (wr == 0) PG8_BAR; }
;     PG8_BAR;
; __global__ void __launch_bounds__(NWAVES * 64, 2) fwd_kernel(Args args) {
;     ...
;         if (G == 256 && bx >= 128) {
;             int tl_ = threadIdx.x; asm volatile("" : "+v"(tl_));
;             convert_weights(args, WI_P1 + WI_OUT, WI_ALL, (bx - 128) * NWAVES + wave, 128 * NWAVES, tl_ & 63);
.LBB0_404:
	v_readlane_b32 s76, v254, 38
	v_readlane_b32 s79, v254, 41
	s_mov_b64 s[72:73], s[84:85]
	s_mov_b32 s79, s88
	s_mov_b32 s84, s89
	v_readlane_b32 s92, v254, 36
	v_readlane_b32 s94, v254, 34
	v_readlane_b32 s96, v254, 32
	v_readlane_b32 s70, v254, 27
	v_readlane_b32 s88, v254, 30
	v_readlane_b32 s77, v254, 39
	v_readlane_b32 s78, v254, 40
	v_readlane_b32 s93, v254, 37
	v_readlane_b32 s95, v254, 35
	v_readlane_b32 s97, v254, 33
	v_readlane_b32 s71, v254, 28
	v_readlane_b32 s89, v254, 31
	v_readlane_b32 s85, v254, 29
	s_barrier
